# up-GEMM K-loop: fragment LDS reads issued inside the preceding compute segment behind their last use (m-major MFMA order), load segments carry only the DMAs; DMA waits retire one segment earlier
# baseline (speedup 1.0000x reference)
; #define PG8_STAGE(bufoff, gbase, voff) do { _Pragma("unroll") for (int _i = 0; _i < 2; ++_i) \
;         __builtin_amdgcn_global_load_lds((const unsigned*)((const char*)(gbase) + (voff)[_i]), (PG8_LAS unsigned*)(lds + (bufoff) + ldsw + _i * 8192), 16, 0, 0); } while (0)
; #define PG8_LDA(dst, b, h) do { _Pragma("unroll") for (int m = 0; m < 4; ++m) _Pragma("unroll") for (int k = 0; k < 2; ++k) dst[m][k] = *(const PG8_LAS bf16x8*)(lds + PG8_SA(b, h) + aoff + m * 2048 + k * 1024); } while (0)
; #define PG8_LDB(dst, b, h) do { _Pragma("unroll") for (int n = 0; n < 2; ++n) _Pragma("unroll") for (int k = 0; k < 2; ++k) dst[n][k] = *(const PG8_LAS bf16x8*)(lds + PG8_SB(b, h) + boff + n * 2048 + k * 1024); } while (0)
; #define PG8_SCHED __builtin_amdgcn_sched_barrier(0)
; template <class Epi, class Sched, bool ALIGN_EPI = false, bool SP2 = false>
; __device__ __forceinline__ void gemm_phase(PG8_LAS unsigned char* lds, const Gemm g, const Sched& S, const Epi& E) {
;     ...
;         const bool has_next = S.next(ui + 1, nxt);
;         const char* nA = has_next ? (const char*)g.A + (size_t)nxt.pm * tstep : cA; const char* nB = has_next ? (const char*)g.Bt + (size_t)nxt.pn * tstep : cB;
;         for (int t = 0; t < nt; t += 2) {
;             const bool last = (t == nt - 2);
;             const char* a1 = cA + (size_t)(t + 1) * kstep;
;             const char* a2 = last ? nA : cA + (size_t)(t + 2) * kstep; const char* b2 = last ? nB : cB + (size_t)(t + 2) * kstep;
;             const char* a3 = a2 + kstep; const char* b3 = b2 + kstep;
;             if (last && has_next) S.a_ready(nxt);
;             if constexpr (SP2) {
;             PG8_LDB(B0, 0, 0); PG8_LDB(B1, 0, 1); PG8_SCHED; PG8_LDA(At, 0, 0); PG8_STAGE(PG8_SA(1, 1), a1 + hstep, voffA);
;     ...
; #pragma unroll
;         for (int a = 0; a < 2; ++a)
; #pragma unroll
;             for (int b = 0; b < 2; ++b)
; #pragma unroll
;                 for (int m = 0; m < 4; ++m)
; #pragma unroll
;                     for (int n = 0; n < 2; ++n) acc[a][b][m][n] = (f32x4){0.f, 0.f, 0.f, 0.f};
;         cur = nxt; cA = nA; cB = nB; ++ui;
.LBB0_54:
	s_ashr_i32 s27, s26, 31
	s_lshl_b64 s[28:29], s[26:27], 20
	s_add_u32 s36, s74, s28
	s_addc_u32 s37, s75, s29
	s_and_b64 s[28:29], s[40:41], exec
	s_cselect_b32 s27, s37, s43
	s_cselect_b32 s65, s36, s42
	s_ashr_i32 s25, s24, 31
	s_lshl_b64 s[28:29], s[24:25], 20
	s_add_u32 s38, s2, s28
	s_addc_u32 s39, s7, s29
	s_and_b64 s[28:29], s[40:41], exec
	s_cselect_b32 s25, s39, s51
	s_cselect_b32 s66, s38, s50
	s_add_u32 s42, s42, 0x80080
	s_addc_u32 s43, s43, 0
	s_add_u32 s67, s50, 0x100
	v_mov_b32_e32 v0, 0
	s_addc_u32 s70, s51, 0
	s_mov_b32 s71, -2
	v_mov_b32_e32 v1, v0
	v_mov_b32_e32 v2, v0
	v_mov_b32_e32 v3, v0
	v_mov_b32_e32 v4, v0
	v_mov_b32_e32 v5, v0
	v_mov_b32_e32 v6, v0
	v_mov_b32_e32 v7, v0
	v_mov_b32_e32 v16, v0
	v_mov_b32_e32 v17, v0
	v_mov_b32_e32 v18, v0
	v_mov_b32_e32 v19, v0
	v_mov_b32_e32 v20, v0
	v_mov_b32_e32 v21, v0
	v_mov_b32_e32 v22, v0
	v_mov_b32_e32 v23, v0
	v_mov_b32_e32 v32, v0
	v_mov_b32_e32 v33, v0
	v_mov_b32_e32 v34, v0
	v_mov_b32_e32 v35, v0
	v_mov_b32_e32 v36, v0
	v_mov_b32_e32 v37, v0
	v_mov_b32_e32 v38, v0
	v_mov_b32_e32 v39, v0
	v_mov_b32_e32 v48, v0
	v_mov_b32_e32 v49, v0
	v_mov_b32_e32 v50, v0
	v_mov_b32_e32 v51, v0
	v_mov_b32_e32 v52, v0
	v_mov_b32_e32 v53, v0
	v_mov_b32_e32 v54, v0
	v_mov_b32_e32 v55, v0
	v_mov_b32_e32 v8, v0
	v_mov_b32_e32 v9, v0
	v_mov_b32_e32 v10, v0
	v_mov_b32_e32 v11, v0
	v_mov_b32_e32 v12, v0
	v_mov_b32_e32 v13, v0
	v_mov_b32_e32 v14, v0
	v_mov_b32_e32 v15, v0
	v_mov_b32_e32 v24, v0
	v_mov_b32_e32 v25, v0
	v_mov_b32_e32 v26, v0
	v_mov_b32_e32 v27, v0
	v_mov_b32_e32 v28, v0
	v_mov_b32_e32 v29, v0
	v_mov_b32_e32 v30, v0
	v_mov_b32_e32 v31, v0
	v_mov_b32_e32 v40, v0
	v_mov_b32_e32 v41, v0
	v_mov_b32_e32 v42, v0
	v_mov_b32_e32 v43, v0
	v_mov_b32_e32 v44, v0
	v_mov_b32_e32 v45, v0
	v_mov_b32_e32 v46, v0
	v_mov_b32_e32 v47, v0
	v_mov_b32_e32 v56, v0
	v_mov_b32_e32 v57, v0
	v_mov_b32_e32 v58, v0
	v_mov_b32_e32 v59, v0
	v_mov_b32_e32 v60, v0
	v_mov_b32_e32 v61, v0
	v_mov_b32_e32 v62, v0
	v_mov_b32_e32 v63, v0
	v_mov_b32_e32 v80, v0
	v_mov_b32_e32 v81, v0
	v_mov_b32_e32 v82, v0
	v_mov_b32_e32 v83, v0
	v_mov_b32_e32 v84, v0
	v_mov_b32_e32 v85, v0
	v_mov_b32_e32 v86, v0
	v_mov_b32_e32 v87, v0
	v_mov_b32_e32 v96, v0
	v_mov_b32_e32 v97, v0
	v_mov_b32_e32 v98, v0
	v_mov_b32_e32 v99, v0
	v_mov_b32_e32 v100, v0
	v_mov_b32_e32 v101, v0
	v_mov_b32_e32 v102, v0
	v_mov_b32_e32 v103, v0
	v_mov_b32_e32 v112, v0
	v_mov_b32_e32 v113, v0
	v_mov_b32_e32 v114, v0
	v_mov_b32_e32 v115, v0
	v_mov_b32_e32 v116, v0
	v_mov_b32_e32 v117, v0
	v_mov_b32_e32 v118, v0
	v_mov_b32_e32 v119, v0
	v_mov_b32_e32 v128, v0
	v_mov_b32_e32 v129, v0
	v_mov_b32_e32 v130, v0
	v_mov_b32_e32 v131, v0
	v_mov_b32_e32 v132, v0
	v_mov_b32_e32 v133, v0
	v_mov_b32_e32 v134, v0
	v_mov_b32_e32 v135, v0
	v_mov_b32_e32 v88, v0
	v_mov_b32_e32 v89, v0
	v_mov_b32_e32 v90, v0
	v_mov_b32_e32 v91, v0
	v_mov_b32_e32 v92, v0
	v_mov_b32_e32 v93, v0
	v_mov_b32_e32 v94, v0
	v_mov_b32_e32 v95, v0
	v_mov_b32_e32 v104, v0
	v_mov_b32_e32 v105, v0
	v_mov_b32_e32 v106, v0
	v_mov_b32_e32 v107, v0
	v_mov_b32_e32 v108, v0
	v_mov_b32_e32 v109, v0
	v_mov_b32_e32 v110, v0
	v_mov_b32_e32 v111, v0
	v_mov_b32_e32 v120, v0
	v_mov_b32_e32 v121, v0
	v_mov_b32_e32 v122, v0
	v_mov_b32_e32 v123, v0
	v_mov_b32_e32 v124, v0
	v_mov_b32_e32 v125, v0
	v_mov_b32_e32 v126, v0
	v_mov_b32_e32 v127, v0
	v_mov_b32_e32 v136, v0
	v_mov_b32_e32 v137, v0
	v_mov_b32_e32 v138, v0
	v_mov_b32_e32 v139, v0
	v_mov_b32_e32 v140, v0
	v_mov_b32_e32 v141, v0
	v_mov_b32_e32 v142, v0
	v_mov_b32_e32 v143, v0
	s_nop 0
	s_nop 0
	s_nop 0
	s_nop 0
	s_nop 0
	s_nop 0
	s_nop 0
	s_nop 0
	v_add_u32_e32 v192, 0x10000, v163
	v_add_u32_e32 v193, 0x14000, v163
	v_add_u32_e32 v212, 0x18000, v163
	v_add_u32_e32 v213, 0x1c000, v163
	ds_read_b128 v[64:67], v192
	ds_read_b128 v[68:71], v192 offset:1024
	ds_read_b128 v[72:75], v192 offset:2048
	ds_read_b128 v[76:79], v192 offset:3072
	ds_read_b128 v[156:159], v193
	ds_read_b128 v[168:171], v193 offset:1024
	ds_read_b128 v[172:175], v193 offset:2048
	ds_read_b128 v[176:179], v193 offset:3072
	ds_read_b128 v[180:183], v165
	ds_read_b128 v[184:187], v165 offset:1024
	ds_read_b128 v[188:191], v165 offset:2048
	ds_read_b128 v[196:199], v165 offset:3072
	ds_read_b128 v[200:203], v165 offset:4096
	ds_read_b128 v[204:207], v165 offset:5120
	ds_read_b128 v[208:211], v165 offset:6144
	ds_read_b128 v[222:225], v165 offset:7168
; #define PG8_STAGE(bufoff, gbase, voff) do { _Pragma("unroll") for (int _i = 0; _i < 2; ++_i) \
;         __builtin_amdgcn_global_load_lds((const unsigned*)((const char*)(gbase) + (voff)[_i]), (PG8_LAS unsigned*)(lds + (bufoff) + ldsw + _i * 8192), 16, 0, 0); } while (0)
; #define PG8_LDA(dst, b, h) do { _Pragma("unroll") for (int m = 0; m < 4; ++m) _Pragma("unroll") for (int k = 0; k < 2; ++k) dst[m][k] = *(const PG8_LAS bf16x8*)(lds + PG8_SA(b, h) + aoff + m * 2048 + k * 1024); } while (0)
; #define PG8_LDB(dst, b, h) do { _Pragma("unroll") for (int n = 0; n < 2; ++n) _Pragma("unroll") for (int k = 0; k < 2; ++k) dst[n][k] = *(const PG8_LAS bf16x8*)(lds + PG8_SB(b, h) + boff + n * 2048 + k * 1024); } while (0)
; #define PG8_MMA(ai, bj, At, Bt) do { __builtin_amdgcn_s_setprio(1); _Pragma("unroll") for (int m = 0; m < 4; ++m) _Pragma("unroll") for (int n = 0; n < 2; ++n) _Pragma("unroll") for (int k = 0; k < 2; ++k) \
;         acc[ai][bj][m][n] = __builtin_amdgcn_mfma_f32_16x16x32_bf16(Bt[n][k], At[m][k], acc[ai][bj][m][n], 0, 0, 0); __builtin_amdgcn_s_setprio(0); } while (0)
; #define PG8_WAIT_V(n) asm volatile("s_waitcnt vmcnt(" #n ")" ::: "memory")
; #define PG8_WAIT_L(n) asm volatile("s_waitcnt lgkmcnt(" #n ")" ::: "memory")
; #define PG8_BAR __builtin_amdgcn_s_barrier()
; #define PG8_SCHED __builtin_amdgcn_sched_barrier(0)
; template <class Epi, class Sched, bool ALIGN_EPI = false, bool SP2 = false>
; __device__ __forceinline__ void gemm_phase(PG8_LAS unsigned char* lds, const Gemm g, const Sched& S, const Epi& E) {
;     ...
;             PG8_LDB(B0, 0, 0); PG8_LDB(B1, 0, 1); PG8_SCHED; PG8_LDA(At, 0, 0); PG8_STAGE(PG8_SA(1, 1), a1 + hstep, voffA);
;             PG8_WAIT_V(8); PG8_WAIT_L(0); PG8_BAR; PG8_MMA(0, 0, At, B0); PG8_MMA(0, 1, At, B1); PG8_BAR; PG8_SCHED;
;             PG8_LDA(At, 0, 1); PG8_STAGE(PG8_SB(0, 0), b2, voffB); PG8_STAGE(PG8_SB(0, 1), b2 + hstep, voffB); PG8_STAGE(PG8_SA(0, 0), a2, voffA);
;             PG8_WAIT_V(8); PG8_WAIT_L(0); PG8_BAR; PG8_MMA(1, 0, At, B0); PG8_MMA(1, 1, At, B1); PG8_BAR; PG8_SCHED;
.LBB0_55:
	s_add_u32 s28, s42, 0xfff80080
	s_addc_u32 s29, s43, -1
	s_add_i32 s72, 0, 0x10000
	s_cmp_eq_u32 s71, 28
	s_cselect_b32 s53, s27, s29
	s_cselect_b32 s52, s65, s28
	s_cselect_b32 s51, s25, s70
	s_cselect_b32 s50, s66, s67
	s_add_i32 s73, 0, 0x14000
	s_add_i32 m0, s12, 0xc000
	s_nop 0
	global_load_lds_dwordx4 v152, s[42:43]
	s_add_i32 m0, s12, 0xe000
	s_nop 0
	global_load_lds_dwordx4 v154, s[42:43]
	s_waitcnt vmcnt(2)
	s_waitcnt lgkmcnt(0)
	s_barrier
	s_setprio 1
	s_waitcnt lgkmcnt(0)
	v_mfma_f32_16x16x32_bf16 v[140:143], v[64:67], v[180:183], v[140:143]
	v_mfma_f32_16x16x32_bf16 v[140:143], v[68:71], v[184:187], v[140:143]
	v_mfma_f32_16x16x32_bf16 v[136:139], v[72:75], v[180:183], v[136:139]
	v_mfma_f32_16x16x32_bf16 v[136:139], v[76:79], v[184:187], v[136:139]
	v_mfma_f32_16x16x32_bf16 v[132:135], v[156:159], v[180:183], v[132:135]
	v_mfma_f32_16x16x32_bf16 v[132:135], v[168:171], v[184:187], v[132:135]
	v_mfma_f32_16x16x32_bf16 v[128:131], v[172:175], v[180:183], v[128:131]
	v_mfma_f32_16x16x32_bf16 v[128:131], v[176:179], v[184:187], v[128:131]
	ds_read_b128 v[180:183], v165 offset:16384
	ds_read_b128 v[184:187], v165 offset:17408
	v_mfma_f32_16x16x32_bf16 v[124:127], v[64:67], v[188:191], v[124:127]
	v_mfma_f32_16x16x32_bf16 v[124:127], v[68:71], v[196:199], v[124:127]
	v_mfma_f32_16x16x32_bf16 v[120:123], v[72:75], v[188:191], v[120:123]
	v_mfma_f32_16x16x32_bf16 v[120:123], v[76:79], v[196:199], v[120:123]
	v_mfma_f32_16x16x32_bf16 v[116:119], v[156:159], v[188:191], v[116:119]
	v_mfma_f32_16x16x32_bf16 v[116:119], v[168:171], v[196:199], v[116:119]
	v_mfma_f32_16x16x32_bf16 v[112:115], v[172:175], v[188:191], v[112:115]
	v_mfma_f32_16x16x32_bf16 v[112:115], v[176:179], v[196:199], v[112:115]
	ds_read_b128 v[188:191], v165 offset:18432
	ds_read_b128 v[196:199], v165 offset:19456
	v_mfma_f32_16x16x32_bf16 v[108:111], v[64:67], v[200:203], v[108:111]
	v_mfma_f32_16x16x32_bf16 v[108:111], v[68:71], v[204:207], v[108:111]
	v_mfma_f32_16x16x32_bf16 v[104:107], v[72:75], v[200:203], v[104:107]
	v_mfma_f32_16x16x32_bf16 v[104:107], v[76:79], v[204:207], v[104:107]
	v_mfma_f32_16x16x32_bf16 v[100:103], v[156:159], v[200:203], v[100:103]
	v_mfma_f32_16x16x32_bf16 v[100:103], v[168:171], v[204:207], v[100:103]
	v_mfma_f32_16x16x32_bf16 v[96:99], v[172:175], v[200:203], v[96:99]
	v_mfma_f32_16x16x32_bf16 v[96:99], v[176:179], v[204:207], v[96:99]
	ds_read_b128 v[200:203], v165 offset:20480
	ds_read_b128 v[204:207], v165 offset:21504
	v_mfma_f32_16x16x32_bf16 v[92:95], v[64:67], v[208:211], v[92:95]
	v_mfma_f32_16x16x32_bf16 v[92:95], v[68:71], v[222:225], v[92:95]
	v_mfma_f32_16x16x32_bf16 v[88:91], v[72:75], v[208:211], v[88:91]
	v_mfma_f32_16x16x32_bf16 v[88:91], v[76:79], v[222:225], v[88:91]
	v_mfma_f32_16x16x32_bf16 v[84:87], v[156:159], v[208:211], v[84:87]
	v_mfma_f32_16x16x32_bf16 v[84:87], v[168:171], v[222:225], v[84:87]
	v_mfma_f32_16x16x32_bf16 v[80:83], v[172:175], v[208:211], v[80:83]
	v_mfma_f32_16x16x32_bf16 v[80:83], v[176:179], v[222:225], v[80:83]
	ds_read_b128 v[208:211], v165 offset:22528
	ds_read_b128 v[222:225], v165 offset:23552
	s_setprio 0
	s_barrier
	s_add_i32 s28, s72, s8
	s_mov_b32 m0, s28
	s_nop 0
	global_load_lds_dwordx4 v194, s[50:51]
	s_add_i32 m0, s28, 0x2000
	s_add_u32 s28, s50, 0x80000
	s_addc_u32 s29, s51, 0
	s_add_i32 s72, s73, s8
	global_load_lds_dwordx4 v144, s[50:51]
	s_mov_b32 m0, s72
	s_nop 0
	global_load_lds_dwordx4 v194, s[28:29]
	s_add_i32 m0, s72, 0x2000
	s_nop 0
	global_load_lds_dwordx4 v144, s[28:29]
	s_mov_b32 m0, s12
	s_nop 0
	global_load_lds_dwordx4 v148, s[52:53]
	s_mov_b32 m0, s20
	s_nop 0
	global_load_lds_dwordx4 v146, s[52:53]
	s_waitcnt vmcnt(6)
	s_waitcnt lgkmcnt(0)
	s_barrier
	s_setprio 1
	s_waitcnt lgkmcnt(0)
	v_mfma_f32_16x16x32_bf16 v[60:63], v[64:67], v[180:183], v[60:63]
	v_mfma_f32_16x16x32_bf16 v[60:63], v[68:71], v[184:187], v[60:63]
	v_mfma_f32_16x16x32_bf16 v[56:59], v[72:75], v[180:183], v[56:59]
	v_mfma_f32_16x16x32_bf16 v[56:59], v[76:79], v[184:187], v[56:59]
	v_mfma_f32_16x16x32_bf16 v[52:55], v[156:159], v[180:183], v[52:55]
	v_mfma_f32_16x16x32_bf16 v[52:55], v[168:171], v[184:187], v[52:55]
	v_mfma_f32_16x16x32_bf16 v[48:51], v[172:175], v[180:183], v[48:51]
	v_mfma_f32_16x16x32_bf16 v[48:51], v[176:179], v[184:187], v[48:51]
	ds_read_b128 v[180:183], v165 offset:32768
	ds_read_b128 v[184:187], v165 offset:33792
	v_mfma_f32_16x16x32_bf16 v[44:47], v[64:67], v[188:191], v[44:47]
	v_mfma_f32_16x16x32_bf16 v[44:47], v[68:71], v[196:199], v[44:47]
	v_mfma_f32_16x16x32_bf16 v[40:43], v[72:75], v[188:191], v[40:43]
	v_mfma_f32_16x16x32_bf16 v[40:43], v[76:79], v[196:199], v[40:43]
	v_mfma_f32_16x16x32_bf16 v[36:39], v[156:159], v[188:191], v[36:39]
	v_mfma_f32_16x16x32_bf16 v[36:39], v[168:171], v[196:199], v[36:39]
	v_mfma_f32_16x16x32_bf16 v[32:35], v[172:175], v[188:191], v[32:35]
	v_mfma_f32_16x16x32_bf16 v[32:35], v[176:179], v[196:199], v[32:35]
	ds_read_b128 v[188:191], v165 offset:34816
	ds_read_b128 v[196:199], v165 offset:35840
	v_mfma_f32_16x16x32_bf16 v[28:31], v[64:67], v[200:203], v[28:31]
	v_mfma_f32_16x16x32_bf16 v[28:31], v[68:71], v[204:207], v[28:31]
	v_mfma_f32_16x16x32_bf16 v[24:27], v[72:75], v[200:203], v[24:27]
	v_mfma_f32_16x16x32_bf16 v[24:27], v[76:79], v[204:207], v[24:27]
	v_mfma_f32_16x16x32_bf16 v[20:23], v[156:159], v[200:203], v[20:23]
	v_mfma_f32_16x16x32_bf16 v[20:23], v[168:171], v[204:207], v[20:23]
	v_mfma_f32_16x16x32_bf16 v[16:19], v[172:175], v[200:203], v[16:19]
	v_mfma_f32_16x16x32_bf16 v[16:19], v[176:179], v[204:207], v[16:19]
	ds_read_b128 v[200:203], v165 offset:36864
	ds_read_b128 v[204:207], v165 offset:37888
	v_mfma_f32_16x16x32_bf16 v[12:15], v[64:67], v[208:211], v[12:15]
	v_mfma_f32_16x16x32_bf16 v[12:15], v[68:71], v[222:225], v[12:15]
	v_mfma_f32_16x16x32_bf16 v[8:11], v[72:75], v[208:211], v[8:11]
	v_mfma_f32_16x16x32_bf16 v[8:11], v[76:79], v[222:225], v[8:11]
	ds_read_b128 v[64:67], v212
	ds_read_b128 v[68:71], v212 offset:1024
	ds_read_b128 v[72:75], v212 offset:2048
	ds_read_b128 v[76:79], v212 offset:3072
	v_mfma_f32_16x16x32_bf16 v[4:7], v[156:159], v[208:211], v[4:7]
	v_mfma_f32_16x16x32_bf16 v[4:7], v[168:171], v[222:225], v[4:7]
	v_mfma_f32_16x16x32_bf16 v[0:3], v[172:175], v[208:211], v[0:3]
	v_mfma_f32_16x16x32_bf16 v[0:3], v[176:179], v[222:225], v[0:3]
	ds_read_b128 v[208:211], v165 offset:38912
	ds_read_b128 v[222:225], v165 offset:39936
	ds_read_b128 v[156:159], v213
	ds_read_b128 v[168:171], v213 offset:1024
	ds_read_b128 v[172:175], v213 offset:2048
	ds_read_b128 v[176:179], v213 offset:3072
	s_setprio 0
	s_barrier
; #define PG8_STAGE(bufoff, gbase, voff) do { _Pragma("unroll") for (int _i = 0; _i < 2; ++_i) \
;         __builtin_amdgcn_global_load_lds((const unsigned*)((const char*)(gbase) + (voff)[_i]), (PG8_LAS unsigned*)(lds + (bufoff) + ldsw + _i * 8192), 16, 0, 0); } while (0)
; #define PG8_LDA(dst, b, h) do { _Pragma("unroll") for (int m = 0; m < 4; ++m) _Pragma("unroll") for (int k = 0; k < 2; ++k) dst[m][k] = *(const PG8_LAS bf16x8*)(lds + PG8_SA(b, h) + aoff + m * 2048 + k * 1024); } while (0)
; #define PG8_LDB(dst, b, h) do { _Pragma("unroll") for (int n = 0; n < 2; ++n) _Pragma("unroll") for (int k = 0; k < 2; ++k) dst[n][k] = *(const PG8_LAS bf16x8*)(lds + PG8_SB(b, h) + boff + n * 2048 + k * 1024); } while (0)
; #define PG8_MMA(ai, bj, At, Bt) do { __builtin_amdgcn_s_setprio(1); _Pragma("unroll") for (int m = 0; m < 4; ++m) _Pragma("unroll") for (int n = 0; n < 2; ++n) _Pragma("unroll") for (int k = 0; k < 2; ++k) \
;         acc[ai][bj][m][n] = __builtin_amdgcn_mfma_f32_16x16x32_bf16(Bt[n][k], At[m][k], acc[ai][bj][m][n], 0, 0, 0); __builtin_amdgcn_s_setprio(0); } while (0)
; #define PG8_WAIT_V(n) asm volatile("s_waitcnt vmcnt(" #n ")" ::: "memory")
; #define PG8_WAIT_L(n) asm volatile("s_waitcnt lgkmcnt(" #n ")" ::: "memory")
; #define PG8_BAR __builtin_amdgcn_s_barrier()
; #define PG8_SCHED __builtin_amdgcn_sched_barrier(0)
; template <class Epi, class Sched, bool ALIGN_EPI = false, bool SP2 = false>
; __device__ __forceinline__ void gemm_phase(PG8_LAS unsigned char* lds, const Gemm g, const Sched& S, const Epi& E) {
;     ...
;             PG8_LDB(B0, 1, 0); PG8_LDB(B1, 1, 1); PG8_SCHED; PG8_LDA(At, 1, 0); PG8_STAGE(PG8_SA(0, 1), a2 + hstep, voffA);
;             PG8_WAIT_V(8); PG8_WAIT_L(0); PG8_BAR; PG8_MMA(0, 0, At, B0); PG8_MMA(0, 1, At, B1); PG8_BAR; PG8_SCHED;
;             PG8_LDA(At, 1, 1); PG8_STAGE(PG8_SB(1, 0), b3, voffB); PG8_STAGE(PG8_SB(1, 1), b3 + hstep, voffB); PG8_STAGE(PG8_SA(1, 0), a3, voffA);
;             PG8_WAIT_V(8); PG8_WAIT_L(0); PG8_BAR; PG8_MMA(1, 0, At, B0); PG8_MMA(1, 1, At, B1); PG8_BAR; PG8_SCHED;
;     ...
;         if constexpr (ALIGN_EPI) { if (wr == 0) PG8_BAR; }
	s_add_i32 s72, 0, 0x18000
	s_add_i32 s73, 0, 0x1c000
	s_add_u32 s28, s52, 0x80000
	s_addc_u32 s29, s53, 0
	s_mov_b32 m0, s21
	s_nop 0
	global_load_lds_dwordx4 v148, s[28:29]
	s_mov_b32 m0, s48
	s_nop 0
	global_load_lds_dwordx4 v146, s[28:29]
	s_waitcnt vmcnt(2)
	s_waitcnt lgkmcnt(0)
	s_barrier
	s_setprio 1
	s_waitcnt lgkmcnt(0)
	v_mfma_f32_16x16x32_bf16 v[140:143], v[64:67], v[180:183], v[140:143]
	v_mfma_f32_16x16x32_bf16 v[140:143], v[68:71], v[184:187], v[140:143]
	v_mfma_f32_16x16x32_bf16 v[136:139], v[72:75], v[180:183], v[136:139]
	v_mfma_f32_16x16x32_bf16 v[136:139], v[76:79], v[184:187], v[136:139]
	v_mfma_f32_16x16x32_bf16 v[132:135], v[156:159], v[180:183], v[132:135]
	v_mfma_f32_16x16x32_bf16 v[132:135], v[168:171], v[184:187], v[132:135]
	v_mfma_f32_16x16x32_bf16 v[128:131], v[172:175], v[180:183], v[128:131]
	v_mfma_f32_16x16x32_bf16 v[128:131], v[176:179], v[184:187], v[128:131]
	ds_read_b128 v[180:183], v165 offset:49152
	ds_read_b128 v[184:187], v165 offset:50176
	v_mfma_f32_16x16x32_bf16 v[124:127], v[64:67], v[188:191], v[124:127]
	v_mfma_f32_16x16x32_bf16 v[124:127], v[68:71], v[196:199], v[124:127]
	v_mfma_f32_16x16x32_bf16 v[120:123], v[72:75], v[188:191], v[120:123]
	v_mfma_f32_16x16x32_bf16 v[120:123], v[76:79], v[196:199], v[120:123]
	v_mfma_f32_16x16x32_bf16 v[116:119], v[156:159], v[188:191], v[116:119]
	v_mfma_f32_16x16x32_bf16 v[116:119], v[168:171], v[196:199], v[116:119]
	v_mfma_f32_16x16x32_bf16 v[112:115], v[172:175], v[188:191], v[112:115]
	v_mfma_f32_16x16x32_bf16 v[112:115], v[176:179], v[196:199], v[112:115]
	ds_read_b128 v[188:191], v165 offset:51200
	ds_read_b128 v[196:199], v165 offset:52224
	v_mfma_f32_16x16x32_bf16 v[108:111], v[64:67], v[200:203], v[108:111]
	v_mfma_f32_16x16x32_bf16 v[108:111], v[68:71], v[204:207], v[108:111]
	v_mfma_f32_16x16x32_bf16 v[104:107], v[72:75], v[200:203], v[104:107]
	v_mfma_f32_16x16x32_bf16 v[104:107], v[76:79], v[204:207], v[104:107]
	v_mfma_f32_16x16x32_bf16 v[100:103], v[156:159], v[200:203], v[100:103]
	v_mfma_f32_16x16x32_bf16 v[100:103], v[168:171], v[204:207], v[100:103]
	v_mfma_f32_16x16x32_bf16 v[96:99], v[172:175], v[200:203], v[96:99]
	v_mfma_f32_16x16x32_bf16 v[96:99], v[176:179], v[204:207], v[96:99]
	ds_read_b128 v[200:203], v165 offset:53248
	ds_read_b128 v[204:207], v165 offset:54272
	v_mfma_f32_16x16x32_bf16 v[92:95], v[64:67], v[208:211], v[92:95]
	v_mfma_f32_16x16x32_bf16 v[92:95], v[68:71], v[222:225], v[92:95]
	v_mfma_f32_16x16x32_bf16 v[88:91], v[72:75], v[208:211], v[88:91]
	v_mfma_f32_16x16x32_bf16 v[88:91], v[76:79], v[222:225], v[88:91]
	v_mfma_f32_16x16x32_bf16 v[84:87], v[156:159], v[208:211], v[84:87]
	v_mfma_f32_16x16x32_bf16 v[84:87], v[168:171], v[222:225], v[84:87]
	v_mfma_f32_16x16x32_bf16 v[80:83], v[172:175], v[208:211], v[80:83]
	v_mfma_f32_16x16x32_bf16 v[80:83], v[176:179], v[222:225], v[80:83]
	ds_read_b128 v[208:211], v165 offset:55296
	ds_read_b128 v[222:225], v165 offset:56320
	s_setprio 0
	s_barrier
	s_add_i32 s28, s72, s8
	s_add_u32 s98, s50, 0x80
	s_addc_u32 s99, s51, 0
	s_mov_b32 m0, s28
	s_nop 0
	global_load_lds_dwordx4 v194, s[98:99]
	s_add_i32 m0, s28, 0x2000
	s_add_u32 s28, s50, 0x80080
	s_addc_u32 s29, s51, 0
	s_add_i32 s50, s73, s8
	global_load_lds_dwordx4 v144, s[98:99]
	s_mov_b32 m0, s50
	s_add_u32 s100, s52, 0x80
	s_addc_u32 s101, s53, 0
	global_load_lds_dwordx4 v194, s[28:29]
	s_add_i32 m0, s50, 0x2000
	s_nop 0
	global_load_lds_dwordx4 v144, s[28:29]
	s_mov_b32 m0, s55
	s_nop 0
	global_load_lds_dwordx4 v148, s[100:101]
	s_mov_b32 m0, s60
	s_nop 0
	global_load_lds_dwordx4 v146, s[100:101]
	s_waitcnt vmcnt(6)
	s_waitcnt lgkmcnt(0)
	s_barrier
	s_setprio 1
	s_waitcnt lgkmcnt(0)
	v_mfma_f32_16x16x32_bf16 v[60:63], v[64:67], v[180:183], v[60:63]
	v_mfma_f32_16x16x32_bf16 v[60:63], v[68:71], v[184:187], v[60:63]
	v_mfma_f32_16x16x32_bf16 v[56:59], v[72:75], v[180:183], v[56:59]
	v_mfma_f32_16x16x32_bf16 v[56:59], v[76:79], v[184:187], v[56:59]
	v_mfma_f32_16x16x32_bf16 v[52:55], v[156:159], v[180:183], v[52:55]
	v_mfma_f32_16x16x32_bf16 v[52:55], v[168:171], v[184:187], v[52:55]
	v_mfma_f32_16x16x32_bf16 v[48:51], v[172:175], v[180:183], v[48:51]
	v_mfma_f32_16x16x32_bf16 v[48:51], v[176:179], v[184:187], v[48:51]
	ds_read_b128 v[180:183], v165
	ds_read_b128 v[184:187], v165 offset:1024
	v_mfma_f32_16x16x32_bf16 v[44:47], v[64:67], v[188:191], v[44:47]
	v_mfma_f32_16x16x32_bf16 v[44:47], v[68:71], v[196:199], v[44:47]
	v_mfma_f32_16x16x32_bf16 v[40:43], v[72:75], v[188:191], v[40:43]
	v_mfma_f32_16x16x32_bf16 v[40:43], v[76:79], v[196:199], v[40:43]
	v_mfma_f32_16x16x32_bf16 v[36:39], v[156:159], v[188:191], v[36:39]
	v_mfma_f32_16x16x32_bf16 v[36:39], v[168:171], v[196:199], v[36:39]
	v_mfma_f32_16x16x32_bf16 v[32:35], v[172:175], v[188:191], v[32:35]
	v_mfma_f32_16x16x32_bf16 v[32:35], v[176:179], v[196:199], v[32:35]
	ds_read_b128 v[188:191], v165 offset:2048
	ds_read_b128 v[196:199], v165 offset:3072
	v_mfma_f32_16x16x32_bf16 v[28:31], v[64:67], v[200:203], v[28:31]
	v_mfma_f32_16x16x32_bf16 v[28:31], v[68:71], v[204:207], v[28:31]
	v_mfma_f32_16x16x32_bf16 v[24:27], v[72:75], v[200:203], v[24:27]
	v_mfma_f32_16x16x32_bf16 v[24:27], v[76:79], v[204:207], v[24:27]
	v_mfma_f32_16x16x32_bf16 v[20:23], v[156:159], v[200:203], v[20:23]
	v_mfma_f32_16x16x32_bf16 v[20:23], v[168:171], v[204:207], v[20:23]
	v_mfma_f32_16x16x32_bf16 v[16:19], v[172:175], v[200:203], v[16:19]
	v_mfma_f32_16x16x32_bf16 v[16:19], v[176:179], v[204:207], v[16:19]
	ds_read_b128 v[200:203], v165 offset:4096
	ds_read_b128 v[204:207], v165 offset:5120
	v_mfma_f32_16x16x32_bf16 v[12:15], v[64:67], v[208:211], v[12:15]
	v_mfma_f32_16x16x32_bf16 v[12:15], v[68:71], v[222:225], v[12:15]
	v_mfma_f32_16x16x32_bf16 v[8:11], v[72:75], v[208:211], v[8:11]
	v_mfma_f32_16x16x32_bf16 v[8:11], v[76:79], v[222:225], v[8:11]
	ds_read_b128 v[64:67], v192
	ds_read_b128 v[68:71], v192 offset:1024
	ds_read_b128 v[72:75], v192 offset:2048
	ds_read_b128 v[76:79], v192 offset:3072
	v_mfma_f32_16x16x32_bf16 v[4:7], v[156:159], v[208:211], v[4:7]
	v_mfma_f32_16x16x32_bf16 v[4:7], v[168:171], v[222:225], v[4:7]
	v_mfma_f32_16x16x32_bf16 v[0:3], v[172:175], v[208:211], v[0:3]
	v_mfma_f32_16x16x32_bf16 v[0:3], v[176:179], v[222:225], v[0:3]
	ds_read_b128 v[208:211], v165 offset:6144
	ds_read_b128 v[222:225], v165 offset:7168
	ds_read_b128 v[156:159], v193
	ds_read_b128 v[168:171], v193 offset:1024
	ds_read_b128 v[172:175], v193 offset:2048
	ds_read_b128 v[176:179], v193 offset:3072
	s_setprio 0
	s_barrier
	s_add_i32 s71, s71, 2
	s_add_u32 s42, s42, 0x100
	s_addc_u32 s43, s43, 0
	s_add_u32 s67, s67, 0x100
	s_addc_u32 s70, s70, 0
	s_cmp_gt_u32 s71, 29
	s_cbranch_scc0 .LBB0_55
	s_waitcnt lgkmcnt(0)
	s_and_b64 vcc, exec, s[22:23]
	s_cbranch_vccz .LBB0_58
	s_barrier
